# GEMM unit decode: the in-group division by the row-group size (always 8 for 256 row tiles) is an arithmetic shift instead of the float-reciprocal sequence, 8 sites
# baseline (speedup 1.0000x reference)
;     __device__ bool next(int i, Unit& u) const {
;         const long L = (long)i * G + c; if (L >= nwg) return false;
;         int wgid = (int)L; { const int q = nwg / NXCD, r = nwg % NXCD, xcd = wgid % NXCD, off = wgid / NXCD; wgid = (xcd < r ? xcd * (q + 1) : r * (q + 1) + (xcd - r) * q) + off; }
;         const int nig = WGM * nN, gid = wgid / nig, fm = gid * WGM, gsz = (nM - fm) < WGM ? (nM - fm) : WGM;
;         u.pm = fm + ((wgid % nig) % gsz); u.pn = (wgid % nig) / gsz; return true;
.LBB0_170:
	s_add_i32 s84, s84, 1
	s_mul_i32 s15, s84, s95
	s_mul_hi_u32 s16, s84, s36
	s_add_i32 s16, s16, s15
	s_mul_i32 s15, s84, s36
	s_add_u32 s28, s15, s2
	s_addc_u32 s29, s16, s33
	v_cmp_gt_i64_e32 vcc, s[28:29], v[196:197]
	v_cmp_lt_i64_e64 s[40:41], s[28:29], v[194:195]
	s_cbranch_vccnz .LBB0_172
	s_ashr_i32 s15, s28, 31
	s_lshr_b32 s15, s15, 29
	s_add_i32 s15, s28, s15
	s_ashr_i32 s16, s15, 3
	s_and_b32 s15, s15, -8
	s_sub_i32 s15, s28, s15
	s_cmp_lt_i32 s15, 0
	s_movk_i32 s22, 0x2c1
	s_cselect_b32 s26, s22, 0x2c0
	s_mul_i32 s15, s15, s26
	s_add_i32 s15, s15, s16
	s_mul_hi_i32 s16, s15, 0x2e8ba2e9
	s_lshr_b32 s26, s16, 31
	s_ashr_i32 s16, s16, 5
	s_add_i32 s16, s16, s26
	s_lshl_b32 s26, s16, 3
	s_sub_i32 s28, 0x100, s26
	s_min_i32 s28, s28, 8
	s_mulk_i32 s16, 0xb0
	s_sub_i32 s15, s15, s16
	s_nop 0
	s_ashr_i32 s85, s15, 3
	s_mul_i32 s16, s85, s28
	s_sub_i32 s15, s15, s16
	s_add_i32 s88, s26, s15

;     __device__ bool next(int i, Unit& u) const {
;         const long L = (long)i * G + c; if (L >= nwg) return false;
;         int wgid = (int)L; { const int q = nwg / NXCD, r = nwg % NXCD, xcd = wgid % NXCD, off = wgid / NXCD; wgid = (xcd < r ? xcd * (q + 1) : r * (q + 1) + (xcd - r) * q) + off; }
;         const int nig = WGM * nN, gid = wgid / nig, fm = gid * WGM, gsz = (nM - fm) < WGM ? (nM - fm) : WGM;
;         u.pm = fm + ((wgid % nig) % gsz); u.pn = (wgid % nig) / gsz; return true;
.LBB0_289:
	s_ashr_i32 s15, s15, 3
	s_add_i32 s15, s26, s15
	s_ashr_i32 s16, s15, 31
	s_lshr_b32 s16, s16, 27
	s_add_i32 s16, s15, s16
	s_ashr_i32 s26, s16, 5
	s_lshl_b32 s26, s26, 3
	s_sub_i32 s28, 0x100, s26
	s_min_i32 s28, s28, 8
	s_andn2_b32 s16, s16, 31
	s_sub_i32 s15, s15, s16
	s_nop 0
	s_ashr_i32 s90, s15, 3
	s_mul_i32 s16, s90, s28
	s_sub_i32 s15, s15, s16
	s_add_i32 s91, s26, s15

;     __device__ bool next(int i, Unit& u) const {
;         const long L = (long)i * G + c; if (L >= nwg) return false;
;         int wgid = (int)L; { const int q = nwg / NXCD, r = nwg % NXCD, xcd = wgid % NXCD, off = wgid / NXCD; wgid = (xcd < r ? xcd * (q + 1) : r * (q + 1) + (xcd - r) * q) + off; }
;         const int nig = WGM * nN, gid = wgid / nig, fm = gid * WGM, gsz = (nM - fm) < WGM ? (nM - fm) : WGM;
;         u.pm = fm + ((wgid % nig) % gsz); u.pn = (wgid % nig) / gsz; return true;
.LBB0_420:
	s_add_i32 s85, s85, 1
	s_mul_i32 s15, s85, s95
	s_mul_hi_u32 s16, s85, s36
	s_add_i32 s16, s16, s15
	s_mul_i32 s15, s85, s36
	s_add_u32 s28, s15, s2
	s_addc_u32 s29, s16, s33
	v_mov_b64_e32 v[2:3], 0xf00
	v_cmp_lt_i64_e64 s[46:47], s[28:29], v[2:3]
	v_mov_b64_e32 v[2:3], 0xeff
	v_cmp_gt_i64_e32 vcc, s[28:29], v[2:3]
	s_cbranch_vccnz .LBB0_422
	s_ashr_i32 s15, s28, 31
	s_lshr_b32 s15, s15, 29
	s_add_i32 s15, s28, s15
	s_ashr_i32 s16, s15, 3
	s_and_b32 s15, s15, -8
	s_sub_i32 s15, s28, s15
	s_cmp_lt_i32 s15, 0
	s_cselect_b32 s26, s54, 0x1e0
	s_mul_i32 s15, s15, s26
	s_add_i32 s15, s15, s16
	s_mul_hi_i32 s16, s15, 0x88888889
	s_add_i32 s16, s16, s15
	s_lshr_b32 s26, s16, 31
	s_ashr_i32 s16, s16, 6
	s_add_i32 s16, s16, s26
	s_lshl_b32 s26, s16, 3
	s_sub_i32 s28, 0x100, s26
	s_min_i32 s28, s28, 8
	s_mulk_i32 s16, 0x78
	s_sub_i32 s15, s15, s16
	s_nop 0
	s_ashr_i32 s88, s15, 3
	s_mul_i32 s16, s88, s28
	s_sub_i32 s15, s15, s16
	s_add_i32 s89, s26, s15

;     __device__ bool next(int i, Unit& u) const {
;         const long L = (long)i * G + c; if (L >= nwg) return false;
;         int wgid = (int)L; { const int q = nwg / NXCD, r = nwg % NXCD, xcd = wgid % NXCD, off = wgid / NXCD; wgid = (xcd < r ? xcd * (q + 1) : r * (q + 1) + (xcd - r) * q) + off; }
;         const int nig = WGM * nN, gid = wgid / nig, fm = gid * WGM, gsz = (nM - fm) < WGM ? (nM - fm) : WGM;
;         u.pm = fm + ((wgid % nig) % gsz); u.pn = (wgid % nig) / gsz; return true;
.LBB0_1432:
	s_add_i32 s85, s85, 1
	s_mul_i32 s15, s85, s95
	s_mul_hi_u32 s16, s85, s36
	s_add_i32 s16, s16, s15
	s_mul_i32 s15, s85, s36
	s_add_u32 s28, s15, s2
	s_addc_u32 s29, s16, s33
	v_mov_b64_e32 v[2:3], 0xc00
	v_cmp_gt_i64_e32 vcc, s[28:29], v[204:205]
	v_cmp_lt_i64_e64 s[46:47], s[28:29], v[2:3]
	s_cbranch_vccnz .LBB0_1434
	s_ashr_i32 s15, s28, 31
	s_lshr_b32 s15, s15, 29
	s_add_i32 s15, s28, s15
	s_ashr_i32 s16, s15, 3
	s_and_b32 s15, s15, -8
	s_sub_i32 s15, s28, s15
	s_cmp_lt_i32 s15, 0
	s_cselect_b32 s26, s54, 0x180
	s_mul_i32 s15, s15, s26
	s_add_i32 s15, s15, s16
	s_mul_hi_i32 s16, s15, 0x2aaaaaab
	s_lshr_b32 s26, s16, 31
	s_ashr_i32 s16, s16, 4
	s_add_i32 s16, s16, s26
	s_lshl_b32 s26, s16, 3
	s_sub_i32 s28, 0x100, s26
	s_min_i32 s28, s28, 8
	s_mulk_i32 s16, 0x60
	s_sub_i32 s15, s15, s16
	s_nop 0
	s_ashr_i32 s88, s15, 3
	s_mul_i32 s16, s88, s28
	s_sub_i32 s15, s15, s16
	s_add_i32 s89, s26, s15

;     __device__ bool next(int i, Unit& u) const {
;     ...
;         const int nig = WGM * nN, gid = wgid / nig, fm = gid * WGM, gsz = (nM - fm) < WGM ? (nM - fm) : WGM;
;         u.pm = fm + ((wgid % nig) % gsz); u.pn = (wgid % nig) / gsz; return true;
.LBB0_1549:
	s_ashr_i32 s16, s16, 3
	s_add_i32 s16, s44, s16
	s_ashr_i32 s26, s16, 31
	s_lshr_b32 s26, s26, 27
	s_add_i32 s26, s16, s26
	s_ashr_i32 s28, s26, 5
	s_lshl_b32 s28, s28, 3
	s_sub_i32 s29, 0x100, s28
	s_min_i32 s29, s29, 8
	s_andn2_b32 s26, s26, 31
	s_sub_i32 s16, s16, s26
	s_mul_i32 s15, s15, -3
	s_ashr_i32 s26, s16, 3
	s_mul_i32 s29, s26, s29
	s_add_i32 s15, s15, s85
	s_sub_i32 s16, s16, s29
	s_mul_i32 s29, s15, 0x101
	s_add_i32 s16, s16, s29
	s_lshl_b32 s15, s15, 2
	s_add_i32 s88, s16, s28
	s_add_i32 s89, s26, s15

;     __device__ bool next(int i, Unit& u) const {
;         const long L = (long)i * G + c; if (L >= nwg) return false;
;         int wgid = (int)L; { const int q = nwg / NXCD, r = nwg % NXCD, xcd = wgid % NXCD, off = wgid / NXCD; wgid = (xcd < r ? xcd * (q + 1) : r * (q + 1) + (xcd - r) * q) + off; }
;         const int nig = WGM * nN, gid = wgid / nig, fm = gid * WGM, gsz = (nM - fm) < WGM ? (nM - fm) : WGM;
;         u.pm = fm + ((wgid % nig) % gsz); u.pn = (wgid % nig) / gsz; return true;
.LBB0_1900:
	s_add_i32 s85, s85, 1
	s_mul_i32 s15, s85, s95
	s_mul_hi_u32 s16, s85, s36
	s_add_i32 s16, s16, s15
	s_mul_i32 s15, s85, s36
	s_add_u32 s28, s15, s2
	s_addc_u32 s29, s16, s33
	v_cmp_gt_i64_e32 vcc, s[28:29], v[196:197]
	v_cmp_lt_i64_e64 s[44:45], s[28:29], v[194:195]
	s_cbranch_vccnz .LBB0_1902
	s_ashr_i32 s15, s28, 31
	s_lshr_b32 s15, s15, 29
	s_add_i32 s15, s28, s15
	s_ashr_i32 s16, s15, 3
	s_and_b32 s15, s15, -8
	s_sub_i32 s15, s28, s15
	s_cmp_lt_i32 s15, 0
	s_movk_i32 s26, 0x2c1
	s_cselect_b32 s26, s26, 0x2c0
	s_mul_i32 s15, s15, s26
	s_add_i32 s15, s15, s16
	s_mul_hi_i32 s16, s15, 0x2e8ba2e9
	s_lshr_b32 s26, s16, 31
	s_ashr_i32 s16, s16, 5
	s_add_i32 s16, s16, s26
	s_lshl_b32 s26, s16, 3
	s_sub_i32 s28, 0x100, s26
	s_min_i32 s28, s28, 8
	s_mulk_i32 s16, 0xb0
	s_sub_i32 s15, s15, s16
	s_nop 0
	s_ashr_i32 s88, s15, 3
	s_mul_i32 s16, s88, s28
	s_sub_i32 s15, s15, s16
	s_add_i32 s89, s26, s15

;     __device__ bool next(int i, Unit& u) const {
;         const long L = (long)i * G + c; if (L >= nwg) return false;
;         int wgid = (int)L; { const int q = nwg / NXCD, r = nwg % NXCD, xcd = wgid % NXCD, off = wgid / NXCD; wgid = (xcd < r ? xcd * (q + 1) : r * (q + 1) + (xcd - r) * q) + off; }
;         const int nig = WGM * nN, gid = wgid / nig, fm = gid * WGM, gsz = (nM - fm) < WGM ? (nM - fm) : WGM;
;         u.pm = fm + ((wgid % nig) % gsz); u.pn = (wgid % nig) / gsz; return true;
.LBB0_2019:
	s_ashr_i32 s15, s15, 3
	s_add_i32 s15, s26, s15
	s_ashr_i32 s16, s15, 31
	s_lshr_b32 s16, s16, 27
	s_add_i32 s16, s15, s16
	s_ashr_i32 s26, s16, 5
	s_lshl_b32 s26, s26, 3
	s_sub_i32 s28, 0x100, s26
	s_min_i32 s28, s28, 8
	s_andn2_b32 s16, s16, 31
	s_sub_i32 s15, s15, s16
	s_nop 0
	s_ashr_i32 s88, s15, 3
	s_mul_i32 s16, s88, s28
	s_sub_i32 s15, s15, s16
	s_add_i32 s89, s26, s15
